# scan-phase tail work only on the workgroups that do not share a CU with a latent scan; partner workgroups keep one latent-attention item
# speedup vs baseline: 1.0116x; 1.0116x over previous
.LBB0_275:
	v_readlane_b32 s12, v227, 0
	s_nop 0
	s_add_i32 s2, s12, 0xffffff80
	s_add_i32 s3, s12, 0xffffff00
	s_cmpk_lt_u32 s3, 0x80
	s_cselect_b32 s12, 0xffff, s3
	s_cmpk_lt_u32 s2, 0x80
	s_cselect_b32 s12, s2, s12
	s_cmpk_lt_u32 s12, 0xc0
	s_cbranch_scc0 .Lg4_ret
	v_writelane_b32 v224, s12, 43
	s_mov_b32 s2, 1
	v_writelane_b32 v224, s2, 42
	v_readlane_b32 s28, v224, 34
	v_readlane_b32 s29, v224, 35
	v_readlane_b32 s38, v224, 36
	s_mov_b32 s16, 0x1ffffc0
	s_mov_b64 s[52:53], 0x2000
	s_mov_b64 s[40:41], 0x4000
	s_mov_b64 s[42:43], 0x6000
	s_mov_b64 s[56:57], 0x2080
	s_mov_b64 s[58:59], 0x4080
	s_mov_b64 s[72:73], 0x6080
	s_movk_i32 s66, 0x2400
	s_movk_i32 s67, 0x90
	s_waitcnt vmcnt(0) lgkmcnt(0)
	s_barrier
	s_branch .Lg4_entry
.Lg4_ret:
	v_readlane_b32 s58, v224, 36
	v_readlane_b32 s59, v227, 0
	s_movk_i32 s60, 0x3d8
	s_mov_b32 s61, 0
	s_nop 0
	s_cmp_eq_u32 s58, 3
	s_cselect_b32 s60, 0x3c0, s60
	s_add_i32 s2, s59, 0xffffff80
	s_add_i32 s3, s59, 0xffffff00
	s_cmpk_lt_u32 s3, 0x80
	s_cselect_b32 s59, 0xffff, s3
	s_cmpk_lt_u32 s2, 0x80
	s_cselect_b32 s59, s2, s59
	s_movk_i32 s38, 0x100

.Ltr_done:
	s_waitcnt vmcnt(0)
	s_cmp_eq_u32 s61, 0
	s_cbranch_scc0 .Ltr_ret_prep
	s_load_dwordx2 s[56:57], s[100:101], 0x110
	s_load_dwordx2 s[84:85], s[100:101], 0x1b0
	s_load_dwordx2 s[72:73], s[100:101], 0x218
	v_readlane_b32 s59, v227, 0
	v_readfirstlane_b32 s60, v131
	s_nop 0
	s_add_i32 s2, s59, 0xffffff80
	s_add_i32 s3, s59, 0xffffff00
	s_cmpk_lt_u32 s3, 0x80
	s_cselect_b32 s59, 0xffff, s3
	s_cmpk_lt_u32 s2, 0x80
	s_cselect_b32 s59, s2, s59
	s_lshl_b32 s59, s59, 2
	s_lshr_b32 s60, s60, 6
	s_add_i32 s59, s59, s60
	s_movk_i32 s60, 0x1600
	v_and_b32_e32 v2, 63, v131
	v_lshlrev_b32_e32 v3, 6, v2
	v_lshlrev_b32_e32 v2, 5, v2
	v_add_u32_e32 v4, 0x6000, v3
	v_add_u32_e32 v5, 0xc000, v3
	v_add_u32_e32 v6, 0x12000, v3
	v_add_u32_e32 v7, 0x18000, v3
	s_waitcnt lgkmcnt(0)
	s_mul_i32 s20, s58, 0xb00000
	s_add_u32 s56, s56, s20
	s_addc_u32 s57, s57, 0
	s_mul_i32 s20, s58, 0x1e000
	s_add_u32 s84, s84, s20
	s_addc_u32 s85, s85, 0
	s_mul_i32 s20, s58, 0x1b800
	s_add_u32 s72, s72, s20
	s_addc_u32 s73, s73, 0
	s_add_u32 s84, s84, 0x3000
	s_addc_u32 s85, s85, 0
.Lb_loop:
	s_cmp_ge_u32 s59, s60
	s_cbranch_scc1 .Ltr_ret_scan
	s_lshl_b32 s66, s59, 11
	s_add_u32 s2, s56, s66
	s_addc_u32 s3, s57, 0
	s_lshl_b32 s66, s59, 2
	s_add_u32 s64, s72, s66
	s_addc_u32 s65, s73, 0
	global_load_dwordx4 v[10:13], v2, s[2:3]
	global_load_dwordx4 v[14:17], v2, s[2:3] offset:16
	global_load_dwordx4 v[40:43], v3, s[84:85] offset:0
	global_load_dwordx4 v[44:47], v3, s[84:85] offset:16
	global_load_dwordx4 v[48:51], v3, s[84:85] offset:32
	global_load_dwordx4 v[52:55], v3, s[84:85] offset:48
	global_load_dwordx4 v[56:59], v4, s[84:85] offset:0
	global_load_dwordx4 v[60:63], v4, s[84:85] offset:16
	global_load_dwordx4 v[64:67], v4, s[84:85] offset:32
	global_load_dwordx4 v[68:71], v4, s[84:85] offset:48
	global_load_dwordx4 v[72:75], v5, s[84:85] offset:0
	global_load_dwordx4 v[76:79], v5, s[84:85] offset:16
	global_load_dwordx4 v[80:83], v5, s[84:85] offset:32
	global_load_dwordx4 v[84:87], v5, s[84:85] offset:48
	global_load_dwordx4 v[88:91], v6, s[84:85] offset:0
	global_load_dwordx4 v[92:95], v6, s[84:85] offset:16
	global_load_dwordx4 v[96:99], v6, s[84:85] offset:32
	global_load_dwordx4 v[100:103], v6, s[84:85] offset:48
	global_load_dwordx4 v[104:107], v7, s[84:85] offset:0
	global_load_dwordx4 v[108:111], v7, s[84:85] offset:16
	global_load_dwordx4 v[112:115], v7, s[84:85] offset:32
	global_load_dwordx4 v[116:119], v7, s[84:85] offset:48
	s_waitcnt vmcnt(0)
	v_lshrrev_b32_e32 v18, 16, v10
	v_cvt_f32_f16_e32 v20, v10
	v_cvt_f32_f16_e32 v21, v18
	v_lshrrev_b32_e32 v18, 16, v11
	v_cvt_f32_f16_e32 v22, v11
	v_cvt_f32_f16_e32 v23, v18
	v_lshrrev_b32_e32 v18, 16, v12
	v_cvt_f32_f16_e32 v24, v12
	v_cvt_f32_f16_e32 v25, v18
	v_lshrrev_b32_e32 v18, 16, v13
	v_cvt_f32_f16_e32 v26, v13
	v_cvt_f32_f16_e32 v27, v18
	v_lshrrev_b32_e32 v18, 16, v14
	v_cvt_f32_f16_e32 v28, v14
	v_cvt_f32_f16_e32 v29, v18
	v_lshrrev_b32_e32 v18, 16, v15
	v_cvt_f32_f16_e32 v30, v15
	v_cvt_f32_f16_e32 v31, v18
	v_lshrrev_b32_e32 v18, 16, v16
	v_cvt_f32_f16_e32 v32, v16
	v_cvt_f32_f16_e32 v33, v18
	v_lshrrev_b32_e32 v18, 16, v17
	v_cvt_f32_f16_e32 v34, v17
	v_cvt_f32_f16_e32 v35, v18
	v_mul_f32_e32 v120, v40, v20
	v_fmac_f32_e32 v120, v41, v21
	v_fmac_f32_e32 v120, v42, v22
	v_fmac_f32_e32 v120, v43, v23
	v_fmac_f32_e32 v120, v44, v24
	v_fmac_f32_e32 v120, v45, v25
	v_fmac_f32_e32 v120, v46, v26
	v_fmac_f32_e32 v120, v47, v27
	v_fmac_f32_e32 v120, v48, v28
	v_fmac_f32_e32 v120, v49, v29
	v_fmac_f32_e32 v120, v50, v30
	v_fmac_f32_e32 v120, v51, v31
	v_fmac_f32_e32 v120, v52, v32
	v_fmac_f32_e32 v120, v53, v33
	v_fmac_f32_e32 v120, v54, v34
	v_fmac_f32_e32 v120, v55, v35
	v_mul_f32_e32 v121, v56, v20
	v_fmac_f32_e32 v121, v57, v21
	v_fmac_f32_e32 v121, v58, v22
	v_fmac_f32_e32 v121, v59, v23
	v_fmac_f32_e32 v121, v60, v24
	v_fmac_f32_e32 v121, v61, v25
	v_fmac_f32_e32 v121, v62, v26
	v_fmac_f32_e32 v121, v63, v27
	v_fmac_f32_e32 v121, v64, v28
	v_fmac_f32_e32 v121, v65, v29
	v_fmac_f32_e32 v121, v66, v30
	v_fmac_f32_e32 v121, v67, v31
	v_fmac_f32_e32 v121, v68, v32
	v_fmac_f32_e32 v121, v69, v33
	v_fmac_f32_e32 v121, v70, v34
	v_fmac_f32_e32 v121, v71, v35
	v_mul_f32_e32 v122, v72, v20
	v_fmac_f32_e32 v122, v73, v21
	v_fmac_f32_e32 v122, v74, v22
	v_fmac_f32_e32 v122, v75, v23
	v_fmac_f32_e32 v122, v76, v24
	v_fmac_f32_e32 v122, v77, v25
	v_fmac_f32_e32 v122, v78, v26
	v_fmac_f32_e32 v122, v79, v27
	v_fmac_f32_e32 v122, v80, v28
	v_fmac_f32_e32 v122, v81, v29
	v_fmac_f32_e32 v122, v82, v30
	v_fmac_f32_e32 v122, v83, v31
	v_fmac_f32_e32 v122, v84, v32
	v_fmac_f32_e32 v122, v85, v33
	v_fmac_f32_e32 v122, v86, v34
	v_fmac_f32_e32 v122, v87, v35
	v_mul_f32_e32 v123, v88, v20
	v_fmac_f32_e32 v123, v89, v21
	v_fmac_f32_e32 v123, v90, v22
	v_fmac_f32_e32 v123, v91, v23
	v_fmac_f32_e32 v123, v92, v24
	v_fmac_f32_e32 v123, v93, v25
	v_fmac_f32_e32 v123, v94, v26
	v_fmac_f32_e32 v123, v95, v27
	v_fmac_f32_e32 v123, v96, v28
	v_fmac_f32_e32 v123, v97, v29
	v_fmac_f32_e32 v123, v98, v30
	v_fmac_f32_e32 v123, v99, v31
	v_fmac_f32_e32 v123, v100, v32
	v_fmac_f32_e32 v123, v101, v33
	v_fmac_f32_e32 v123, v102, v34
	v_fmac_f32_e32 v123, v103, v35
	v_mul_f32_e32 v124, v104, v20
	v_fmac_f32_e32 v124, v105, v21
	v_fmac_f32_e32 v124, v106, v22
	v_fmac_f32_e32 v124, v107, v23
	v_fmac_f32_e32 v124, v108, v24
	v_fmac_f32_e32 v124, v109, v25
	v_fmac_f32_e32 v124, v110, v26
	v_fmac_f32_e32 v124, v111, v27
	v_fmac_f32_e32 v124, v112, v28
	v_fmac_f32_e32 v124, v113, v29
	v_fmac_f32_e32 v124, v114, v30
	v_fmac_f32_e32 v124, v115, v31
	v_fmac_f32_e32 v124, v116, v32
	v_fmac_f32_e32 v124, v117, v33
	v_fmac_f32_e32 v124, v118, v34
	v_fmac_f32_e32 v124, v119, v35
	s_nop 1
	v_add_f32_dpp v120, v120, v120 quad_perm:[1,0,3,2] row_mask:0xf bank_mask:0xf bound_ctrl:1
	v_add_f32_dpp v121, v121, v121 quad_perm:[1,0,3,2] row_mask:0xf bank_mask:0xf bound_ctrl:1
	v_add_f32_dpp v122, v122, v122 quad_perm:[1,0,3,2] row_mask:0xf bank_mask:0xf bound_ctrl:1
	v_add_f32_dpp v123, v123, v123 quad_perm:[1,0,3,2] row_mask:0xf bank_mask:0xf bound_ctrl:1
	v_add_f32_dpp v124, v124, v124 quad_perm:[1,0,3,2] row_mask:0xf bank_mask:0xf bound_ctrl:1
	s_nop 1
	v_add_f32_dpp v120, v120, v120 quad_perm:[2,3,0,1] row_mask:0xf bank_mask:0xf bound_ctrl:1
	v_add_f32_dpp v121, v121, v121 quad_perm:[2,3,0,1] row_mask:0xf bank_mask:0xf bound_ctrl:1
	v_add_f32_dpp v122, v122, v122 quad_perm:[2,3,0,1] row_mask:0xf bank_mask:0xf bound_ctrl:1
	v_add_f32_dpp v123, v123, v123 quad_perm:[2,3,0,1] row_mask:0xf bank_mask:0xf bound_ctrl:1
	v_add_f32_dpp v124, v124, v124 quad_perm:[2,3,0,1] row_mask:0xf bank_mask:0xf bound_ctrl:1
	s_nop 1
	v_add_f32_dpp v120, v120, v120 row_half_mirror row_mask:0xf bank_mask:0xf bound_ctrl:1
	v_add_f32_dpp v121, v121, v121 row_half_mirror row_mask:0xf bank_mask:0xf bound_ctrl:1
	v_add_f32_dpp v122, v122, v122 row_half_mirror row_mask:0xf bank_mask:0xf bound_ctrl:1
	v_add_f32_dpp v123, v123, v123 row_half_mirror row_mask:0xf bank_mask:0xf bound_ctrl:1
	v_add_f32_dpp v124, v124, v124 row_half_mirror row_mask:0xf bank_mask:0xf bound_ctrl:1
	s_nop 1
	v_add_f32_dpp v120, v120, v120 row_mirror row_mask:0xf bank_mask:0xf bound_ctrl:1
	v_add_f32_dpp v121, v121, v121 row_mirror row_mask:0xf bank_mask:0xf bound_ctrl:1
	v_add_f32_dpp v122, v122, v122 row_mirror row_mask:0xf bank_mask:0xf bound_ctrl:1
	v_add_f32_dpp v123, v123, v123 row_mirror row_mask:0xf bank_mask:0xf bound_ctrl:1
	v_add_f32_dpp v124, v124, v124 row_mirror row_mask:0xf bank_mask:0xf bound_ctrl:1
	s_nop 1
	v_readlane_b32 s66, v120, 0
	v_readlane_b32 s67, v120, 16
	v_readlane_b32 s14, v120, 32
	v_readlane_b32 s15, v120, 48
	s_nop 1
	v_mov_b32_e32 v125, s66
	v_add_f32_e32 v125, s67, v125
	v_add_f32_e32 v125, s14, v125
	v_add_f32_e32 v125, s15, v125
	v_readlane_b32 s66, v121, 0
	v_readlane_b32 s67, v121, 16
	v_readlane_b32 s14, v121, 32
	v_readlane_b32 s15, v121, 48
	s_nop 1
	v_mov_b32_e32 v126, s66
	v_add_f32_e32 v126, s67, v126
	v_add_f32_e32 v126, s14, v126
	v_add_f32_e32 v126, s15, v126
	v_readlane_b32 s66, v122, 0
	v_readlane_b32 s67, v122, 16
	v_readlane_b32 s14, v122, 32
	v_readlane_b32 s15, v122, 48
	s_nop 1
	v_mov_b32_e32 v127, s66
	v_add_f32_e32 v127, s67, v127
	v_add_f32_e32 v127, s14, v127
	v_add_f32_e32 v127, s15, v127
	v_readlane_b32 s66, v123, 0
	v_readlane_b32 s67, v123, 16
	v_readlane_b32 s14, v123, 32
	v_readlane_b32 s15, v123, 48
	s_nop 1
	v_mov_b32_e32 v128, s66
	v_add_f32_e32 v128, s67, v128
	v_add_f32_e32 v128, s14, v128
	v_add_f32_e32 v128, s15, v128
	v_readlane_b32 s66, v124, 0
	v_readlane_b32 s67, v124, 16
	v_readlane_b32 s14, v124, 32
	v_readlane_b32 s15, v124, 48
	s_nop 1
	v_mov_b32_e32 v129, s66
	v_add_f32_e32 v129, s67, v129
	v_add_f32_e32 v129, s14, v129
	v_add_f32_e32 v129, s15, v129
	s_mov_b64 exec, 1
	global_store_dword v1, v125, s[64:65]
	s_add_u32 s64, s64, 0x5800
	s_addc_u32 s65, s65, 0
	global_store_dword v1, v126, s[64:65]
	s_add_u32 s64, s64, 0x5800
	s_addc_u32 s65, s65, 0
	global_store_dword v1, v127, s[64:65]
	s_add_u32 s64, s64, 0x5800
	s_addc_u32 s65, s65, 0
	global_store_dword v1, v128, s[64:65]
	s_add_u32 s64, s64, 0x5800
	s_addc_u32 s65, s65, 0
	global_store_dword v1, v129, s[64:65]
	s_mov_b64 exec, -1
	s_addk_i32 s59, 0x400
	s_branch .Lb_loop
